# HGRN scan: quad partial sums of 4 steps merged by lane-select and written once per 4 steps by all lanes (no exec-masked writes); op_sel broadcast instead of v_mov copies
# speedup vs baseline: 1.0417x; 1.0022x over previous
; #define HG_LD(X, tl_) do { const float* f_ = sF + (tl_) * 128 + seg * 4; const float* q_ = sQ + (tl_) * 128 + seg * 4;   \
;                 X##f0 = *(const f32x4*)(f_); X##f1 = *(const f32x4*)(f_ + 64); X##q0 = *(const f32x4*)(q_); X##q1 = *(const f32x4*)(q_ + 64); \
;                 X##va = sDV[(tl_) * 64 + cp]; X##vb = sDV[(tl_) * 64 + 32 + cp]; } while (0)
; __device__ __forceinline__ void phase_hgrn(KP P, int l_, unsigned char* shm) {
;     ...
;             {
;                 f32x4 Af0, Af1, Aq0, Aq1; float Ava, Avb;
;                 f32x4 Bf0, Bf1, Bq0, Bq1; float Bva, Bvb;
;                 HG_LD(A, 0);
; #pragma unroll 2
;                 for (int tl = 0; tl < T; tl += 2) {
;                     HG_LD(B, tl + 1);
;                     HG_STEP(A, tl);
;                     HG_LD(A, tl + 2);
;                     HG_STEP(B, tl + 1);
;                 }
.LBB0_2162:
	ds_read_b128 v[18:21], v111
	ds_read_b128 v[14:17], v111 offset:256
	ds_read_b128 v[10:13], v111 offset:16384
	ds_read_b128 v[6:9], v111 offset:16640
	ds_read2_b32 v[78:79], v116 offset1:32
	s_mov_b32 s17, -2
	v_mov_b32_e32 v129, v110
	v_mov_b32_e32 v130, v109
	v_and_b32_e32 v133, 3, v228
	v_mul_u32_u24_e32 v133, 0x3ff, v133
	v_add_u32_e32 v135, v107, v133
	v_add_u32_e32 v136, v108, v133
	s_mov_b32 s60, 0x22222222
	s_mov_b32 s61, 0x22222222
	s_mov_b32 s62, 0x44444444
	s_mov_b32 s63, 0x44444444
	s_mov_b32 s64, 0x88888888
	s_mov_b32 s65, 0x88888888
	s_waitcnt lgkmcnt(0)
	s_branch .LBB0_2164
.LBB0_2163:
	s_add_i32 s17, s17, 4
	v_add_u32_e32 v135, 0x1000, v135
	v_add_u32_e32 v136, 0x1000, v136
	v_add_u32_e32 v130, 0x400, v130
	s_cmp_gt_u32 s17, 29
	v_add_u32_e32 v129, 0x800, v129
	s_cbranch_scc1 .LBB0_2172
; #define HG_LD(X, tl_) do { const float* f_ = sF + (tl_) * 128 + seg * 4; const float* q_ = sQ + (tl_) * 128 + seg * 4;   \
;                 X##f0 = *(const f32x4*)(f_); X##f1 = *(const f32x4*)(f_ + 64); X##q0 = *(const f32x4*)(q_); X##q1 = *(const f32x4*)(q_ + 64); \
;                 X##va = sDV[(tl_) * 64 + cp]; X##vb = sDV[(tl_) * 64 + 32 + cp]; } while (0)
; __device__ __forceinline__ void phase_hgrn(KP P, int l_, unsigned char* shm) {
;     ...
;             {
;                 f32x4 Af0, Af1, Aq0, Aq1; float Ava, Avb;
;                 f32x4 Bf0, Bf1, Bq0, Bq1; float Bva, Bvb;
;                 HG_LD(A, 0);
; #pragma unroll 2
;                 for (int tl = 0; tl < T; tl += 2) {
;                     HG_LD(B, tl + 1);
;                     HG_STEP(A, tl);
;                     HG_LD(A, tl + 2);
;                     HG_STEP(B, tl + 1);
.LBB0_2164:
	ds_read_b128 v[34:37], v129
	ds_read_b128 v[30:33], v129 offset:256
	ds_read_b128 v[26:29], v129 offset:16384
	ds_read_b128 v[22:25], v129 offset:16640
	ds_read2_b32 v[80:81], v130 offset1:32
	s_waitcnt lgkmcnt(8)
	v_pk_fma_f32 v[70:71], v[20:21], v[70:71], v[78:79] op_sel_hi:[1,1,0]
	v_pk_fma_f32 v[76:77], v[20:21], v[76:77], v[78:79] op_sel:[0,0,1]
	v_pk_fma_f32 v[64:65], v[18:19], v[64:65], v[78:79] op_sel_hi:[1,1,0]
	v_pk_fma_f32 v[82:83], v[18:19], v[62:63], v[78:79] op_sel:[0,0,1]
	s_waitcnt lgkmcnt(7)
	v_pk_fma_f32 v[68:69], v[14:15], v[68:69], v[78:79] op_sel_hi:[1,1,0]
	v_pk_fma_f32 v[74:75], v[14:15], v[74:75], v[78:79] op_sel:[0,0,1]
	v_pk_fma_f32 v[66:67], v[16:17], v[66:67], v[78:79] op_sel_hi:[1,1,0]
	v_pk_fma_f32 v[72:73], v[16:17], v[72:73], v[78:79] op_sel:[0,0,1]
	v_pk_mul_f32 v[14:15], v[12:13], v[70:71]
	v_pk_mul_f32 v[12:13], v[12:13], v[76:77]
	v_pk_fma_f32 v[14:15], v[10:11], v[64:65], v[14:15]
	v_pk_fma_f32 v[10:11], v[10:11], v[82:83], v[12:13]
	v_pk_fma_f32 v[12:13], v[8:9], v[66:67], v[14:15]
	v_pk_fma_f32 v[8:9], v[8:9], v[72:73], v[10:11]
	v_pk_fma_f32 v[12:13], v[6:7], v[68:69], v[12:13]
	v_pk_fma_f32 v[6:7], v[6:7], v[74:75], v[8:9]
	v_add_f32_e32 v4, v12, v13
	v_add_f32_e32 v6, v6, v7
	s_nop 0
	v_add_f32_dpp v4, v4, v4 quad_perm:[1,0,3,2] row_mask:0xf bank_mask:0xf bound_ctrl:1
	v_add_f32_dpp v6, v6, v6 quad_perm:[1,0,3,2] row_mask:0xf bank_mask:0xf bound_ctrl:1
	s_nop 0
	v_add_f32_dpp v133, v4, v4 quad_perm:[2,3,0,1] row_mask:0xf bank_mask:0xf bound_ctrl:1
	v_add_f32_dpp v134, v6, v6 quad_perm:[2,3,0,1] row_mask:0xf bank_mask:0xf bound_ctrl:1
	s_waitcnt lgkmcnt(0)
	ds_read_b128 v[18:21], v129 offset:512
	ds_read_b128 v[14:17], v129 offset:768
	ds_read_b128 v[10:13], v129 offset:16896
	ds_read_b128 v[6:9], v129 offset:17152
	ds_read2_b32 v[62:63], v130 offset0:64 offset1:96
	v_pk_fma_f32 v[70:71], v[70:71], v[36:37], v[80:81] op_sel_hi:[1,1,0]
	v_pk_fma_f32 v[76:77], v[36:37], v[76:77], v[80:81] op_sel:[0,0,1]
	v_pk_fma_f32 v[64:65], v[64:65], v[34:35], v[80:81] op_sel_hi:[1,1,0]
	v_pk_fma_f32 v[78:79], v[34:35], v[82:83], v[80:81] op_sel:[0,0,1]
	v_pk_fma_f32 v[82:83], v[68:69], v[30:31], v[80:81] op_sel_hi:[1,1,0]
	v_pk_fma_f32 v[84:85], v[74:75], v[30:31], v[80:81] op_sel:[0,0,1]
	v_pk_fma_f32 v[86:87], v[66:67], v[32:33], v[80:81] op_sel_hi:[1,1,0]
	v_pk_fma_f32 v[88:89], v[72:73], v[32:33], v[80:81] op_sel:[0,0,1]
	v_pk_mul_f32 v[30:31], v[28:29], v[70:71]
	v_pk_mul_f32 v[28:29], v[28:29], v[76:77]
	v_pk_fma_f32 v[30:31], v[26:27], v[64:65], v[30:31]
	v_pk_fma_f32 v[26:27], v[26:27], v[78:79], v[28:29]
	v_pk_fma_f32 v[28:29], v[24:25], v[86:87], v[30:31]
	v_pk_fma_f32 v[24:25], v[24:25], v[88:89], v[26:27]
	v_pk_fma_f32 v[28:29], v[22:23], v[82:83], v[28:29]
	v_pk_fma_f32 v[22:23], v[22:23], v[84:85], v[24:25]
	v_add_f32_e32 v4, v28, v29
	v_add_f32_e32 v22, v22, v23
	s_nop 0
	v_add_f32_dpp v4, v4, v4 quad_perm:[1,0,3,2] row_mask:0xf bank_mask:0xf bound_ctrl:1
	v_add_f32_dpp v22, v22, v22 quad_perm:[1,0,3,2] row_mask:0xf bank_mask:0xf bound_ctrl:1
	s_nop 0
	v_add_f32_dpp v4, v4, v4 quad_perm:[2,3,0,1] row_mask:0xf bank_mask:0xf bound_ctrl:1
	v_add_f32_dpp v22, v22, v22 quad_perm:[2,3,0,1] row_mask:0xf bank_mask:0xf bound_ctrl:1
	v_cndmask_b32_e64 v133, v133, v4, s[60:61]
	v_cndmask_b32_e64 v134, v134, v22, s[60:61]
	s_waitcnt lgkmcnt(0)
	ds_read_b128 v[34:37], v129 offset:1024
	ds_read_b128 v[30:33], v129 offset:1280
	ds_read_b128 v[26:29], v129 offset:17408
	ds_read_b128 v[22:25], v129 offset:17664
	ds_read2_b32 v[66:67], v130 offset0:128 offset1:160
	v_pk_fma_f32 v[70:71], v[20:21], v[70:71], v[62:63] op_sel_hi:[1,1,0]
	v_pk_fma_f32 v[72:73], v[20:21], v[76:77], v[62:63] op_sel:[0,0,1]
	v_pk_fma_f32 v[64:65], v[18:19], v[64:65], v[62:63] op_sel_hi:[1,1,0]
	v_pk_fma_f32 v[68:69], v[18:19], v[78:79], v[62:63] op_sel:[0,0,1]
	v_pk_fma_f32 v[74:75], v[14:15], v[82:83], v[62:63] op_sel_hi:[1,1,0]
	v_pk_fma_f32 v[80:81], v[14:15], v[84:85], v[62:63] op_sel:[0,0,1]
	v_pk_fma_f32 v[82:83], v[16:17], v[86:87], v[62:63] op_sel_hi:[1,1,0]
	v_pk_fma_f32 v[84:85], v[16:17], v[88:89], v[62:63] op_sel:[0,0,1]
	v_pk_mul_f32 v[14:15], v[12:13], v[70:71]
	v_pk_mul_f32 v[12:13], v[12:13], v[72:73]
	v_pk_fma_f32 v[14:15], v[10:11], v[64:65], v[14:15]
	v_pk_fma_f32 v[10:11], v[10:11], v[68:69], v[12:13]
	v_pk_fma_f32 v[12:13], v[8:9], v[82:83], v[14:15]
	v_pk_fma_f32 v[8:9], v[8:9], v[84:85], v[10:11]
	v_pk_fma_f32 v[12:13], v[6:7], v[74:75], v[12:13]
	v_pk_fma_f32 v[6:7], v[6:7], v[80:81], v[8:9]
	v_add_f32_e32 v4, v12, v13
	v_add_f32_e32 v6, v6, v7
	s_nop 0
	v_add_f32_dpp v4, v4, v4 quad_perm:[1,0,3,2] row_mask:0xf bank_mask:0xf bound_ctrl:1
	v_add_f32_dpp v6, v6, v6 quad_perm:[1,0,3,2] row_mask:0xf bank_mask:0xf bound_ctrl:1
	s_nop 0
	v_add_f32_dpp v4, v4, v4 quad_perm:[2,3,0,1] row_mask:0xf bank_mask:0xf bound_ctrl:1
	v_add_f32_dpp v6, v6, v6 quad_perm:[2,3,0,1] row_mask:0xf bank_mask:0xf bound_ctrl:1
	v_cndmask_b32_e64 v133, v133, v4, s[62:63]
	v_cndmask_b32_e64 v134, v134, v6, s[62:63]
	s_waitcnt lgkmcnt(0)
	v_pk_fma_f32 v[70:71], v[70:71], v[36:37], v[66:67] op_sel_hi:[1,1,0]
	v_pk_fma_f32 v[76:77], v[36:37], v[72:73], v[66:67] op_sel:[0,0,1]
	v_pk_fma_f32 v[64:65], v[64:65], v[34:35], v[66:67] op_sel_hi:[1,1,0]
	v_pk_fma_f32 v[62:63], v[34:35], v[68:69], v[66:67] op_sel:[0,0,1]
	v_pk_fma_f32 v[68:69], v[74:75], v[30:31], v[66:67] op_sel_hi:[1,1,0]
	v_pk_fma_f32 v[74:75], v[80:81], v[30:31], v[66:67] op_sel:[0,0,1]
	v_pk_fma_f32 v[72:73], v[84:85], v[32:33], v[66:67] op_sel:[0,0,1]
	v_pk_fma_f32 v[66:67], v[82:83], v[32:33], v[66:67] op_sel_hi:[1,1,0]
	v_pk_mul_f32 v[30:31], v[28:29], v[70:71]
	v_pk_mul_f32 v[28:29], v[28:29], v[76:77]
	v_pk_fma_f32 v[30:31], v[26:27], v[64:65], v[30:31]
	v_pk_fma_f32 v[26:27], v[26:27], v[62:63], v[28:29]
	v_pk_fma_f32 v[28:29], v[24:25], v[66:67], v[30:31]
	v_pk_fma_f32 v[24:25], v[24:25], v[72:73], v[26:27]
	v_pk_fma_f32 v[28:29], v[22:23], v[68:69], v[28:29]
	v_pk_fma_f32 v[22:23], v[22:23], v[74:75], v[24:25]
	v_add_f32_e32 v24, v28, v29
	v_add_f32_e32 v23, v22, v23
	ds_read2_b32 v[78:79], v130 offset0:192 offset1:224
	ds_read_b128 v[18:21], v129 offset:1536
	ds_read_b128 v[14:17], v129 offset:1792
	ds_read_b128 v[10:13], v129 offset:17920
	ds_read_b128 v[6:9], v129 offset:18176
	v_add_f32_dpp v22, v24, v24 quad_perm:[1,0,3,2] row_mask:0xf bank_mask:0xf bound_ctrl:1
	v_add_f32_dpp v23, v23, v23 quad_perm:[1,0,3,2] row_mask:0xf bank_mask:0xf bound_ctrl:1
	s_nop 0
	v_add_f32_dpp v22, v22, v22 quad_perm:[2,3,0,1] row_mask:0xf bank_mask:0xf bound_ctrl:1
	v_add_f32_dpp v23, v23, v23 quad_perm:[2,3,0,1] row_mask:0xf bank_mask:0xf bound_ctrl:1
	v_cndmask_b32_e64 v133, v133, v22, s[64:65]
	v_cndmask_b32_e64 v134, v134, v23, s[64:65]
	ds_write_b32 v135, v133
	ds_write_b32 v136, v134
	s_branch .LBB0_2163
